# attention: MFMA-result wait states before the row max trimmed from 25 to the required 13
# speedup vs baseline: 1.0973x; 1.0008x over previous
.LBB0_1781:
	s_or_b64 exec, exec, s[10:11]
	s_lshl_b32 s53, s20, 2
	s_add_i32 s52, s53, s41
	s_cmp_lt_i32 s52, 0
	s_cbranch_scc1 .LBB0_1785
	v_add_u32_e32 v0, v221, v205
	ds_read_b128 v[2:5], v0
	ds_read_b128 v[18:21], v0 offset:32
	ds_read_b128 v[22:25], v0 offset:6656
	ds_read_b128 v[38:41], v0 offset:6688
	s_waitcnt lgkmcnt(3)
	v_mfma_f32_32x32x16_bf16 v[2:17], v[2:5], v[82:85], 0
	s_waitcnt lgkmcnt(1)
	v_mfma_f32_32x32x16_bf16 v[22:37], v[22:25], v[82:85], 0
	v_mfma_f32_32x32x16_bf16 v[2:17], v[18:21], v[86:89], v[2:17]
	s_waitcnt lgkmcnt(0)
	v_mfma_f32_32x32x16_bf16 v[22:37], v[38:41], v[86:89], v[22:37]
	ds_read_b128 v[18:21], v0 offset:64
	ds_read_b128 v[38:41], v0 offset:96
	s_waitcnt lgkmcnt(1)
	v_mfma_f32_32x32x16_bf16 v[2:17], v[18:21], v[90:93], v[2:17]
	ds_read_b128 v[18:21], v0 offset:6720
	ds_read_b128 v[42:45], v0 offset:6752
	s_waitcnt lgkmcnt(1)
	v_mfma_f32_32x32x16_bf16 v[22:37], v[18:21], v[90:93], v[22:37]
	v_mfma_f32_32x32x16_bf16 v[2:17], v[38:41], v[94:97], v[2:17]
	ds_read_b128 v[18:21], v0 offset:128
	ds_read_b128 v[38:41], v0 offset:160
	s_waitcnt lgkmcnt(2)
	v_mfma_f32_32x32x16_bf16 v[22:37], v[42:45], v[94:97], v[22:37]
	s_waitcnt lgkmcnt(1)
	v_mfma_f32_32x32x16_bf16 v[2:17], v[18:21], v[98:101], v[2:17]
	ds_read_b128 v[18:21], v0 offset:6784
	ds_read_b128 v[42:45], v0 offset:6816
	s_waitcnt lgkmcnt(1)
	v_mfma_f32_32x32x16_bf16 v[22:37], v[18:21], v[98:101], v[22:37]
	v_mfma_f32_32x32x16_bf16 v[2:17], v[38:41], v[102:105], v[2:17]
	s_waitcnt lgkmcnt(0)
	v_mfma_f32_32x32x16_bf16 v[22:37], v[42:45], v[102:105], v[22:37]
	s_nop 11
	s_nop 0
	v_max3_f32 v0, v2, v3, v22
	v_max3_f32 v18, v4, v5, v23
	s_nop 0
	v_max3_f32 v0, v0, v24, v25
	v_max3_f32 v18, v18, v8, v9
	s_nop 0
	v_max3_f32 v0, v0, v6, v7
	v_max3_f32 v18, v18, v28, v29
	s_nop 0
	v_max3_f32 v0, v0, v26, v27
	v_max3_f32 v18, v18, v12, v13
	s_nop 0
	v_max3_f32 v0, v0, v10, v11
	v_max3_f32 v18, v18, v32, v33
	s_nop 0
	v_max3_f32 v0, v0, v30, v31
	v_max3_f32 v18, v18, v16, v17
	s_nop 0
	v_max3_f32 v0, v0, v14, v15
	v_max3_f32 v18, v18, v36, v37
	s_nop 0
	v_max3_f32 v0, v0, v34, v35
	v_max_f32_e32 v18, v18, v18
	v_max_f32_e32 v0, v0, v0
	v_max_f32_e32 v0, v0, v18
	ds_bpermute_b32 v18, v206, v0
	s_waitcnt lgkmcnt(0)
	v_max_f32_e32 v18, v18, v18
	v_max_f32_e32 v38, v0, v18
	v_exp_f32_e64 v52, -v38
	s_and_saveexec_b64 s[10:11], s[6:7]
	ds_write_b32 v207, v52 offset:45056
	s_or_b64 exec, exec, s[10:11]
	v_sub_f32_e32 v0, v2, v38
	v_sub_f32_e32 v2, v22, v38
	v_sub_f32_e32 v3, v3, v38
	v_sub_f32_e32 v18, v23, v38
	v_exp_f32_e32 v72, v0
	v_exp_f32_e32 v78, v2
	v_exp_f32_e32 v0, v3
	v_exp_f32_e32 v48, v18
	v_sub_f32_e32 v4, v4, v38
	v_add_f32_e32 v49, v78, v72
	v_sub_f32_e32 v19, v24, v38
	v_pk_add_f32 v[2:3], v[48:49], v[0:1]
	v_sub_f32_e32 v5, v5, v38
	v_sub_f32_e32 v20, v25, v38
	v_sub_f32_e32 v22, v26, v38
	v_sub_f32_e32 v24, v27, v38
	v_pk_add_f32 v[26:27], v[2:3], v[2:3] op_sel_hi:[0,1]
	v_exp_f32_e32 v49, v4
	v_exp_f32_e32 v79, v19
	v_exp_f32_e32 v26, v5
	v_exp_f32_e32 v58, v20
	v_sub_f32_e32 v21, v6, v38
	v_add_f32_e32 v59, v79, v49
	v_sub_f32_e32 v43, v10, v38
	v_sub_f32_e32 v45, v11, v38
	v_sub_f32_e32 v47, v12, v38
	s_waitcnt lgkmcnt(0)
	v_add_u32_e32 v12, s50, v205
	v_pk_add_f32 v[10:11], v[58:59], v[26:27]
	v_sub_f32_e32 v23, v7, v38
	v_sub_f32_e32 v39, v8, v38
	v_sub_f32_e32 v40, v28, v38
	v_sub_f32_e32 v41, v9, v38
	v_sub_f32_e32 v42, v29, v38
	ds_read_b128 v[2:5], v12 offset:45120
	ds_read_b128 v[6:9], v12 offset:45152
	v_pk_add_f32 v[28:29], v[10:11], v[10:11] op_sel_hi:[0,1]
	v_exp_f32_e32 v27, v21
	v_exp_f32_e32 v59, v22
	v_exp_f32_e32 v28, v23
	v_exp_f32_e32 v60, v24
	v_sub_f32_e32 v76, v16, v38
	v_add_f32_e32 v61, v59, v27
	v_sub_f32_e32 v77, v17, v38
	s_waitcnt lgkmcnt(0)
	v_pk_mul_f32 v[16:17], v[8:9], 0 op_sel_hi:[1,0]
	v_pk_add_f32 v[8:9], v[60:61], v[28:29]
	v_sub_f32_e32 v44, v30, v38
	v_sub_f32_e32 v46, v31, v38
	v_pk_add_f32 v[30:31], v[8:9], v[8:9] op_sel_hi:[0,1]
	v_exp_f32_e32 v29, v39
	v_exp_f32_e32 v39, v40
	v_exp_f32_e32 v30, v41
	v_exp_f32_e32 v62, v42
	v_sub_f32_e32 v53, v13, v38
	v_add_f32_e32 v63, v39, v29
	ds_read_b128 v[18:21], v12 offset:45056
	ds_read_b128 v[22:25], v12 offset:45088
	v_pk_mul_f32 v[12:13], v[4:5], 0 op_sel_hi:[1,0]
	v_pk_add_f32 v[4:5], v[62:63], v[30:31]
	v_sub_f32_e32 v55, v34, v38
	v_sub_f32_e32 v57, v35, v38
	v_pk_add_f32 v[34:35], v[4:5], v[4:5] op_sel_hi:[0,1]
	v_exp_f32_e32 v61, v43
	v_exp_f32_e32 v63, v44
	v_exp_f32_e32 v34, v45
	v_exp_f32_e32 v64, v46
	v_sub_f32_e32 v32, v32, v38
	v_add_f32_e32 v65, v63, v61
	v_sub_f32_e32 v54, v14, v38
	v_sub_f32_e32 v56, v15, v38
	v_pk_mul_f32 v[14:15], v[6:7], 0 op_sel_hi:[1,0]
	v_pk_add_f32 v[6:7], v[64:65], v[34:35]
	v_sub_f32_e32 v33, v33, v38
	v_pk_add_f32 v[66:67], v[6:7], v[6:7] op_sel_hi:[0,1]
	v_exp_f32_e32 v35, v47
	v_exp_f32_e32 v65, v32
	v_exp_f32_e32 v66, v53
	v_exp_f32_e32 v68, v33
	v_pk_mul_f32 v[10:11], v[2:3], 0 op_sel_hi:[1,0]
	v_add_f32_e32 v69, v65, v35
	v_exp_f32_e32 v53, v54
	v_pk_add_f32 v[2:3], v[68:69], v[66:67]
	v_exp_f32_e32 v67, v55
	v_pk_add_f32 v[70:71], v[2:3], v[2:3] op_sel_hi:[0,1]
	v_cvt_pk_bf16_f32 v40, v72, v0
	v_add_u32_e32 v0, 0x3000, v223
	v_cvt_pk_bf16_f32 v41, v49, v26
	v_cvt_pk_bf16_f32 v42, v27, v28
	v_cvt_pk_bf16_f32 v43, v29, v30
	ds_read2_b64 v[44:47], v0 offset0:128 offset1:130
	v_exp_f32_e32 v70, v56
	v_exp_f32_e32 v72, v57
	v_add_f32_e32 v73, v67, v53
	s_waitcnt lgkmcnt(1)
	v_pk_mul_f32 v[8:9], v[24:25], 0 op_sel_hi:[1,0]
	v_pk_mul_f32 v[4:5], v[20:21], 0 op_sel_hi:[1,0]
	v_pk_mul_f32 v[6:7], v[22:23], 0 op_sel_hi:[1,0]
	v_pk_mul_f32 v[2:3], v[18:19], 0 op_sel_hi:[1,0]
	v_pk_add_f32 v[54:55], v[72:73], v[70:71]
	v_add_u32_e32 v49, 0x4000, v223
	s_waitcnt lgkmcnt(0)
	v_mfma_f32_32x32x16_bf16 v[18:33], v[40:43], v[44:47], v[2:17]
	ds_read2_b64 v[44:47], v49 offset0:192 offset1:194
	v_add_f32_e64 v74, v54, v54
	v_add_f32_e64 v75, v54, v55
	v_exp_f32_e32 v69, v76
	v_exp_f32_e32 v74, v77
	ds_read2_b64 v[54:57], v0 offset0:132 offset1:134
	v_add_f32_e32 v173, 0, v38
	s_waitcnt lgkmcnt(1)
	v_mfma_f32_32x32x16_bf16 v[2:17], v[40:43], v[44:47], v[2:17]
	v_cvt_pk_bf16_f32 v40, v61, v34
	v_cvt_pk_bf16_f32 v41, v35, v66
	v_cvt_pk_bf16_f32 v42, v53, v70
	v_cvt_pk_bf16_f32 v43, v69, v74
	ds_read2_b64 v[44:47], v49 offset0:196 offset1:198
	v_sub_f32_e32 v53, v36, v38
	v_sub_f32_e32 v61, v37, v38
	s_waitcnt lgkmcnt(1)
	v_mfma_f32_32x32x16_bf16 v[18:33], v[40:43], v[54:57], v[18:33]
	ds_read2_b64 v[54:57], v49 offset0:200 offset1:202
	v_exp_f32_e32 v53, v53
	v_xor_b32_e32 v34, 0x80000000, v173
	v_mov_b32_e32 v35, v34
	v_mov_b32_e32 v36, v34
	v_mov_b32_e32 v37, v34
	v_mov_b32_e32 v38, v34
	s_waitcnt lgkmcnt(1)
	v_mfma_f32_32x32x16_bf16 v[2:17], v[40:43], v[44:47], v[2:17]
	v_cvt_pk_bf16_f32 v44, v78, v48
	v_cvt_pk_bf16_f32 v45, v79, v58
	v_cvt_pk_bf16_f32 v46, v59, v60
	v_cvt_pk_bf16_f32 v47, v39, v62
	ds_read2_b64 v[40:43], v0 offset0:136 offset1:138
	v_exp_f32_e32 v62, v61
	ds_read2_b64 v[58:61], v0 offset0:140 offset1:142
	s_waitcnt lgkmcnt(1)
	v_mfma_f32_32x32x16_bf16 v[18:33], v[44:47], v[40:43], v[18:33]
	v_mov_b32_e32 v39, v34
	v_mov_b32_e32 v40, v34
	v_mov_b32_e32 v41, v34
	v_mov_b32_e32 v42, v34
	v_mov_b32_e32 v43, v34
	v_mov_b32_e32 v48, v34
	v_mfma_f32_32x32x16_bf16 v[2:17], v[44:47], v[54:57], v[2:17]
	v_cvt_pk_bf16_f32 v54, v63, v64
	v_cvt_pk_bf16_f32 v55, v65, v68
	v_cvt_pk_bf16_f32 v56, v67, v72
	v_cvt_pk_bf16_f32 v57, v53, v62
	v_add_f32_e32 v63, v53, v69
	v_pk_add_f32 v[62:63], v[62:63], v[74:75]
	v_mov_b32_e32 v44, v34
	s_waitcnt lgkmcnt(0)
	v_mfma_f32_32x32x16_bf16 v[18:33], v[54:57], v[58:61], v[18:33]
	ds_read2_b64 v[58:61], v49 offset0:204 offset1:206
	v_add_f32_e32 v224, v62, v63
	v_mov_b32_e32 v45, v34
	v_mov_b32_e32 v46, v34
	v_mov_b32_e32 v47, v34
	v_mov_b32_e32 v49, v34
	v_fmac_f32_e32 v224, 0, v52
	s_waitcnt lgkmcnt(0)
	v_mfma_f32_32x32x16_bf16 v[2:17], v[54:57], v[58:61], v[2:17]
	s_branch .LBB0_1786

.LBB0_1797:
	s_bitcmp1_b32 s10, 0
	s_cselect_b32 s10, 0x5800, 0
	s_add_i32 s56, s10, 0
	v_add3_u32 v0, s56, v204, v205
	ds_read_b128 v[50:53], v0
	ds_read_b128 v[178:181], v0 offset:32
	ds_read_b128 v[182:185], v0 offset:6656
	ds_read_b128 v[186:189], v0 offset:6688
	s_waitcnt lgkmcnt(3)
	v_mfma_f32_32x32x16_bf16 v[66:81], v[50:53], v[82:85], v[34:49]
	s_waitcnt lgkmcnt(1)
	v_mfma_f32_32x32x16_bf16 v[50:65], v[182:185], v[82:85], v[34:49]
	v_mfma_f32_32x32x16_bf16 v[66:81], v[178:181], v[86:89], v[66:81]
	ds_read_b128 v[178:181], v0 offset:64
	ds_read_b128 v[182:185], v0 offset:96
	s_waitcnt lgkmcnt(2)
	v_mfma_f32_32x32x16_bf16 v[50:65], v[186:189], v[86:89], v[50:65]
	s_waitcnt lgkmcnt(1)
	v_mfma_f32_32x32x16_bf16 v[66:81], v[178:181], v[90:93], v[66:81]
	ds_read_b128 v[178:181], v0 offset:6720
	ds_read_b128 v[186:189], v0 offset:6752
	s_waitcnt lgkmcnt(1)
	v_mfma_f32_32x32x16_bf16 v[50:65], v[178:181], v[90:93], v[50:65]
	v_mfma_f32_32x32x16_bf16 v[66:81], v[182:185], v[94:97], v[66:81]
	ds_read_b128 v[178:181], v0 offset:128
	ds_read_b128 v[182:185], v0 offset:160
	s_waitcnt lgkmcnt(2)
	v_mfma_f32_32x32x16_bf16 v[50:65], v[186:189], v[94:97], v[50:65]
	s_waitcnt lgkmcnt(1)
	v_mfma_f32_32x32x16_bf16 v[66:81], v[178:181], v[98:101], v[66:81]
	ds_read_b128 v[178:181], v0 offset:6784
	ds_read_b128 v[186:189], v0 offset:6816
	s_waitcnt lgkmcnt(1)
	v_mfma_f32_32x32x16_bf16 v[50:65], v[178:181], v[98:101], v[50:65]
	v_mfma_f32_32x32x16_bf16 v[66:81], v[182:185], v[102:105], v[66:81]
	s_waitcnt lgkmcnt(0)
	v_mfma_f32_32x32x16_bf16 v[50:65], v[186:189], v[102:105], v[50:65]
	s_nop 11
	s_nop 0
	v_max3_f32 v0, v66, v67, v50
	v_max3_f32 v178, v68, v69, v51
	s_nop 0
	v_max3_f32 v0, v0, v52, v53
	v_max3_f32 v178, v178, v72, v73
	s_nop 0
	v_max3_f32 v0, v0, v70, v71
	v_max3_f32 v178, v178, v56, v57
	s_nop 0
	v_max3_f32 v0, v0, v54, v55
	v_max3_f32 v178, v178, v76, v77
	s_nop 0
	v_max3_f32 v0, v0, v74, v75
	v_max3_f32 v178, v178, v60, v61
	s_nop 0
	v_max3_f32 v0, v0, v58, v59
	v_max3_f32 v178, v178, v80, v81
	s_nop 0
	v_max3_f32 v0, v0, v78, v79
	v_max3_f32 v178, v178, v64, v65
	s_nop 0
	v_max3_f32 v0, v0, v62, v63
	v_max_f32_e32 v178, v178, v178
	v_max_f32_e32 v0, v0, v0
	v_max_f32_e32 v0, v0, v178
	ds_bpermute_b32 v178, v206, v0
	s_waitcnt lgkmcnt(0)
	v_max_f32_e32 v178, v178, v178
	v_max_f32_e32 v0, v0, v178
	v_cmp_lt_f32_e32 vcc, 0x41000000, v0
	s_cbranch_vccz .LBB0_1801
	v_max_f32_e32 v0, v0, v0
	v_max_f32_e32 v0, 0, v0
	v_exp_f32_e64 v225, -v0
	s_and_saveexec_b64 s[10:11], s[6:7]
	ds_write_b32 v207, v225 offset:45056
	s_or_b64 exec, exec, s[10:11]
	v_add_f32_e32 v173, v173, v0
	v_pk_add_f32 v[66:67], v[66:67], v[0:1] op_sel_hi:[1,0] neg_lo:[0,1] neg_hi:[0,1]
	v_pk_add_f32 v[50:51], v[50:51], v[0:1] op_sel_hi:[1,0] neg_lo:[0,1] neg_hi:[0,1]
	v_pk_add_f32 v[68:69], v[68:69], v[0:1] op_sel_hi:[1,0] neg_lo:[0,1] neg_hi:[0,1]
	v_pk_add_f32 v[52:53], v[52:53], v[0:1] op_sel_hi:[1,0] neg_lo:[0,1] neg_hi:[0,1]
	v_pk_add_f32 v[70:71], v[70:71], v[0:1] op_sel_hi:[1,0] neg_lo:[0,1] neg_hi:[0,1]
	v_pk_add_f32 v[54:55], v[54:55], v[0:1] op_sel_hi:[1,0] neg_lo:[0,1] neg_hi:[0,1]
	v_pk_add_f32 v[72:73], v[72:73], v[0:1] op_sel_hi:[1,0] neg_lo:[0,1] neg_hi:[0,1]
	v_pk_add_f32 v[56:57], v[56:57], v[0:1] op_sel_hi:[1,0] neg_lo:[0,1] neg_hi:[0,1]
	v_pk_add_f32 v[74:75], v[74:75], v[0:1] op_sel_hi:[1,0] neg_lo:[0,1] neg_hi:[0,1]
	v_pk_add_f32 v[58:59], v[58:59], v[0:1] op_sel_hi:[1,0] neg_lo:[0,1] neg_hi:[0,1]
	v_pk_add_f32 v[76:77], v[76:77], v[0:1] op_sel_hi:[1,0] neg_lo:[0,1] neg_hi:[0,1]
	v_pk_add_f32 v[60:61], v[60:61], v[0:1] op_sel_hi:[1,0] neg_lo:[0,1] neg_hi:[0,1]
	v_pk_add_f32 v[78:79], v[78:79], v[0:1] op_sel_hi:[1,0] neg_lo:[0,1] neg_hi:[0,1]
	v_pk_add_f32 v[62:63], v[62:63], v[0:1] op_sel_hi:[1,0] neg_lo:[0,1] neg_hi:[0,1]
	v_pk_add_f32 v[80:81], v[80:81], v[0:1] op_sel_hi:[1,0] neg_lo:[0,1] neg_hi:[0,1]
	v_pk_add_f32 v[64:65], v[64:65], v[0:1] op_sel_hi:[1,0] neg_lo:[0,1] neg_hi:[0,1]
	s_waitcnt lgkmcnt(0)
	v_add_u32_e32 v0, s50, v205
	ds_read_b128 v[178:181], v0 offset:45120
	ds_read_b128 v[182:185], v0 offset:45152
	ds_read_b128 v[186:189], v0 offset:45056
	ds_read_b128 v[190:193], v0 offset:45088
	v_xor_b32_e32 v34, 0x80000000, v173
	v_mov_b32_e32 v35, v34
	v_mov_b32_e32 v36, v34
	v_mov_b32_e32 v37, v34
	v_mov_b32_e32 v38, v34
	v_mov_b32_e32 v39, v34
	v_mov_b32_e32 v40, v34
	v_mov_b32_e32 v41, v34
	v_mov_b32_e32 v42, v34
	v_mov_b32_e32 v43, v34
	v_mov_b32_e32 v44, v34
	v_mov_b32_e32 v45, v34
	v_mov_b32_e32 v46, v34
	v_mov_b32_e32 v47, v34
	v_mov_b32_e32 v48, v34
	v_mov_b32_e32 v49, v34
	v_mul_f32_e32 v224, v224, v225
	s_waitcnt lgkmcnt(2)
	v_pk_mul_f32 v[30:31], v[30:31], v[182:183]
	v_pk_mul_f32 v[26:27], v[26:27], v[178:179]
	s_waitcnt lgkmcnt(0)
	v_pk_mul_f32 v[22:23], v[22:23], v[190:191]
	v_pk_mul_f32 v[32:33], v[32:33], v[184:185]
	v_pk_mul_f32 v[28:29], v[28:29], v[180:181]
	v_pk_mul_f32 v[24:25], v[24:25], v[192:193]
	v_pk_mul_f32 v[20:21], v[20:21], v[188:189]
	v_pk_mul_f32 v[18:19], v[18:19], v[186:187]
	v_pk_mul_f32 v[14:15], v[14:15], v[182:183]
	v_pk_mul_f32 v[10:11], v[10:11], v[178:179]
	v_pk_mul_f32 v[6:7], v[6:7], v[190:191]
	v_pk_mul_f32 v[16:17], v[16:17], v[184:185]
	v_pk_mul_f32 v[12:13], v[12:13], v[180:181]
	v_pk_mul_f32 v[8:9], v[8:9], v[192:193]
	v_pk_mul_f32 v[4:5], v[4:5], v[188:189]
	v_pk_mul_f32 v[2:3], v[2:3], v[186:187]
